# P7 sample-tile split-K epilogue: 20 loads issued up front, one wait, atomics stream (was one vmcnt(0) per group behind the atomics)
# baseline (speedup 1.0000x reference)
;     __device__ __forceinline__ void operator()(const f32x4 (&acc)[2][2][4][2], const Unit& u, int wr, int wc, int fr, int fq) const {
;         const int col0 = u.pn * BM + wc * 32 + 4 * fq;
; #pragma unroll
;         for (int m = 0; m < 4; ++m) {
;             const int row = u.pm * BM + wr * 64 + m * 16 + fr;
;             const float rs = rstd[row];
; #pragma unroll
;             for (int bj = 0; bj < 2; ++bj)
; #pragma unroll
;                 for (int n = 0; n < 2; ++n) {
;                     const int c = col0 + bj * HALF + n * 16;
;                     const u32x2e gw = *(const u32x2e*)(GS + (size_t)row * 1024 + c);
;                     const f32x4 a = acc[0][bj][m][n]; float* p = T1 + (size_t)(row - P_ROWS) * 1024 + c;
;                     __hip_atomic_fetch_add(p + 0, a[0] * rs * bf_lo(gw.x), __ATOMIC_RELAXED, __HIP_MEMORY_SCOPE_AGENT); __hip_atomic_fetch_add(p + 1, a[1] * rs * bf_hi(gw.x), __ATOMIC_RELAXED, __HIP_MEMORY_SCOPE_AGENT);
;                     __hip_atomic_fetch_add(p + 2, a[2] * rs * bf_lo(gw.y), __ATOMIC_RELAXED, __HIP_MEMORY_SCOPE_AGENT); __hip_atomic_fetch_add(p + 3, a[3] * rs * bf_hi(gw.y), __ATOMIC_RELAXED, __HIP_MEMORY_SCOPE_AGENT);
;                 }
;         }
.LBB0_1527:
	v_lshl_add_u32 v72, s40, 8, v1
	v_ashrrev_i32_e32 v73, 31, v72
	v_lshl_or_b32 v70, s42, 8, v80
	v_lshl_add_u64 v[74:75], v[72:73], 2, s[14:15]
	v_lshlrev_b64 v[74:75], 11, v[72:73]
	v_ashrrev_i32_e32 v71, 31, v70
	v_lshl_add_u64 v[76:77], s[12:13], 0, v[74:75]
	v_lshlrev_b64 v[74:75], 1, v[70:71]
	v_lshl_add_u64 v[78:79], v[76:77], 0, v[74:75]
	v_lshlrev_b64 v[142:143], 1, v[70:71]
	v_lshl_add_u64 v[144:145], v[72:73], 2, s[14:15]
	global_load_dword v100, v[144:145], off
	v_lshlrev_b64 v[144:145], 11, v[72:73]
	v_lshl_add_u64 v[144:145], s[12:13], 0, v[144:145]
	v_lshl_add_u64 v[144:145], v[144:145], 0, v[142:143]
	global_load_dwordx2 v[104:105], v[144:145], off
	global_load_dwordx2 v[106:107], v[144:145], off offset:32
	global_load_dwordx2 v[108:109], v[144:145], off offset:256
	global_load_dwordx2 v[110:111], v[144:145], off offset:288
	v_or_b32_e32 v146, 16, v72
	v_ashrrev_i32_e32 v147, 31, v146
	v_lshl_add_u64 v[144:145], v[146:147], 2, s[14:15]
	global_load_dword v101, v[144:145], off
	v_lshlrev_b64 v[144:145], 11, v[146:147]
	v_lshl_add_u64 v[144:145], s[12:13], 0, v[144:145]
	v_lshl_add_u64 v[144:145], v[144:145], 0, v[142:143]
	global_load_dwordx2 v[112:113], v[144:145], off
	global_load_dwordx2 v[114:115], v[144:145], off offset:32
	global_load_dwordx2 v[116:117], v[144:145], off offset:256
	global_load_dwordx2 v[118:119], v[144:145], off offset:288
	v_or_b32_e32 v146, 32, v72
	v_ashrrev_i32_e32 v147, 31, v146
	v_lshl_add_u64 v[144:145], v[146:147], 2, s[14:15]
	global_load_dword v102, v[144:145], off
	v_lshlrev_b64 v[144:145], 11, v[146:147]
	v_lshl_add_u64 v[144:145], s[12:13], 0, v[144:145]
	v_lshl_add_u64 v[144:145], v[144:145], 0, v[142:143]
	global_load_dwordx2 v[120:121], v[144:145], off
	global_load_dwordx2 v[122:123], v[144:145], off offset:32
	global_load_dwordx2 v[124:125], v[144:145], off offset:256
	global_load_dwordx2 v[126:127], v[144:145], off offset:288
	v_or_b32_e32 v146, 48, v72
	v_ashrrev_i32_e32 v147, 31, v146
	v_lshl_add_u64 v[144:145], v[146:147], 2, s[14:15]
	global_load_dword v103, v[144:145], off
	v_lshlrev_b64 v[144:145], 11, v[146:147]
	v_lshl_add_u64 v[144:145], s[12:13], 0, v[144:145]
	v_lshl_add_u64 v[144:145], v[144:145], 0, v[142:143]
	global_load_dwordx2 v[128:129], v[144:145], off
	global_load_dwordx2 v[130:131], v[144:145], off offset:32
	global_load_dwordx2 v[132:133], v[144:145], off offset:256
	global_load_dwordx2 v[134:135], v[144:145], off offset:288
	v_lshlrev_b64 v[76:77], 12, v[72:73]
	v_lshl_add_u64 v[76:77], s[8:9], 0, v[76:77]
	s_brev_b32 s27, 15
	v_lshl_add_u64 v[70:71], v[70:71], 2, v[76:77]
	s_brev_b32 s44, 15
	v_add_co_u32_e32 v88, vcc, s27, v70
	s_mov_b32 s45, -1
	s_nop 0
	v_addc_co_u32_e32 v89, vcc, -1, v71, vcc
	v_lshl_add_u64 v[76:77], v[70:71], 0, s[44:45]
	s_mov_b32 s27, 0xf0010000
	s_mov_b32 s44, 0xf0010000
	s_mov_b32 s45, -1
	s_waitcnt vmcnt(0)
	v_mul_f32_e32 v62, v62, v100
	v_mul_f32_e32 v63, v63, v100
	v_mul_f32_e32 v64, v64, v100
	v_mul_f32_e32 v65, v65, v100
	v_mul_f32_e32 v58, v58, v100
	v_mul_f32_e32 v59, v59, v100
	v_lshlrev_b32_e32 v73, 16, v104
	v_and_b32_e32 v86, 0xffff0000, v104
	v_lshlrev_b32_e32 v91, 16, v105
	v_and_b32_e32 v87, 0xffff0000, v105
	v_mul_f32_e32 v62, v62, v73
	v_mul_f32_e32 v63, v63, v86
	v_mul_f32_e32 v64, v64, v91
	v_mul_f32_e32 v65, v65, v87
	global_atomic_add_f32 v[88:89], v62, off
	global_atomic_add_f32 v[76:77], v63, off offset:4
	global_atomic_add_f32 v[76:77], v64, off offset:8
	global_atomic_add_f32 v[76:77], v65, off offset:12
	v_mul_f32_e32 v60, v60, v100
	v_mul_f32_e32 v61, v61, v100
	v_mul_f32_e32 v54, v54, v100
	v_mul_f32_e32 v55, v55, v100
	v_mul_f32_e32 v56, v56, v100
	v_mul_f32_e32 v57, v57, v100
	v_mul_f32_e32 v50, v50, v100
	v_mul_f32_e32 v51, v51, v100
	v_mul_f32_e32 v52, v52, v100
	v_mul_f32_e32 v53, v53, v100
	v_lshlrev_b32_e32 v64, 16, v106
	v_and_b32_e32 v62, 0xffff0000, v106
	v_lshlrev_b32_e32 v65, 16, v107
	v_and_b32_e32 v63, 0xffff0000, v107
	v_mul_f32_e32 v58, v58, v64
	v_mul_f32_e32 v59, v59, v62
	v_mul_f32_e32 v60, v60, v65
	v_mul_f32_e32 v61, v61, v63
	global_atomic_add_f32 v[76:77], v58, off offset:64
	global_atomic_add_f32 v[76:77], v59, off offset:68
	global_atomic_add_f32 v[76:77], v60, off offset:72
	global_atomic_add_f32 v[76:77], v61, off offset:76
	v_lshlrev_b32_e32 v60, 16, v108
	v_and_b32_e32 v58, 0xffff0000, v108
	v_lshlrev_b32_e32 v61, 16, v109
	v_and_b32_e32 v59, 0xffff0000, v109
	v_mul_f32_e32 v54, v54, v60
	v_mul_f32_e32 v55, v55, v58
	v_mul_f32_e32 v56, v56, v61
	v_mul_f32_e32 v57, v57, v59
	global_atomic_add_f32 v[76:77], v54, off offset:512
	global_atomic_add_f32 v[76:77], v55, off offset:516
	global_atomic_add_f32 v[76:77], v56, off offset:520
	global_atomic_add_f32 v[76:77], v57, off offset:524
	v_or_b32_e32 v54, 16, v72
	v_ashrrev_i32_e32 v55, 31, v54
	v_lshl_add_u64 v[58:59], v[54:55], 2, s[14:15]
	v_lshlrev_b64 v[54:55], 11, v[54:55]
	v_lshl_add_u64 v[54:55], s[12:13], 0, v[54:55]
	v_lshl_add_u64 v[54:55], v[54:55], 0, v[74:75]
	v_lshlrev_b32_e32 v60, 16, v110
	v_and_b32_e32 v56, 0xffff0000, v110
	v_lshlrev_b32_e32 v61, 16, v111
	v_and_b32_e32 v57, 0xffff0000, v111
	v_mul_f32_e32 v50, v50, v60
	v_mul_f32_e32 v51, v51, v56
	v_mul_f32_e32 v52, v52, v61
	v_mul_f32_e32 v53, v53, v57
	global_atomic_add_f32 v[76:77], v50, off offset:576
	global_atomic_add_f32 v[76:77], v51, off offset:580
	global_atomic_add_f32 v[76:77], v52, off offset:584
	global_atomic_add_f32 v[76:77], v53, off offset:588
	s_nop 0
	v_add_co_u32_e32 v56, vcc, s27, v70
	v_lshl_add_u64 v[50:51], v[70:71], 0, s[44:45]
	s_nop 0
	v_addc_co_u32_e32 v57, vcc, -1, v71, vcc
	s_mov_b32 s27, 0xf0020000
	s_mov_b32 s44, 0xf0020000
;     __device__ __forceinline__ void operator()(const f32x4 (&acc)[2][2][4][2], const Unit& u, int wr, int wc, int fr, int fq) const {
;     ...
;         for (int m = 0; m < 4; ++m) {
;             const int row = u.pm * BM + wr * 64 + m * 16 + fr;
;             const float rs = rstd[row];
; #pragma unroll
;             for (int bj = 0; bj < 2; ++bj)
; #pragma unroll
;                 for (int n = 0; n < 2; ++n) {
;                     const int c = col0 + bj * HALF + n * 16;
;                     const u32x2e gw = *(const u32x2e*)(GS + (size_t)row * 1024 + c);
;                     const f32x4 a = acc[0][bj][m][n]; float* p = T1 + (size_t)(row - P_ROWS) * 1024 + c;
;                     __hip_atomic_fetch_add(p + 0, a[0] * rs * bf_lo(gw.x), __ATOMIC_RELAXED, __HIP_MEMORY_SCOPE_AGENT); __hip_atomic_fetch_add(p + 1, a[1] * rs * bf_hi(gw.x), __ATOMIC_RELAXED, __HIP_MEMORY_SCOPE_AGENT);
;                     __hip_atomic_fetch_add(p + 2, a[2] * rs * bf_lo(gw.y), __ATOMIC_RELAXED, __HIP_MEMORY_SCOPE_AGENT); __hip_atomic_fetch_add(p + 3, a[3] * rs * bf_hi(gw.y), __ATOMIC_RELAXED, __HIP_MEMORY_SCOPE_AGENT);
;                 }
;         }
	s_mov_b32 s45, -1
	v_mul_f32_e32 v46, v46, v101
	v_lshlrev_b32_e32 v59, 16, v112
	v_mul_f32_e32 v47, v47, v101
	v_and_b32_e32 v52, 0xffff0000, v112
	v_mul_f32_e32 v48, v48, v101
	v_lshlrev_b32_e32 v60, 16, v113
	v_mul_f32_e32 v49, v49, v101
	v_and_b32_e32 v53, 0xffff0000, v113
	v_mul_f32_e32 v46, v46, v59
	v_mul_f32_e32 v47, v47, v52
	v_mul_f32_e32 v48, v48, v60
	v_mul_f32_e32 v49, v49, v53
	global_atomic_add_f32 v[56:57], v46, off
	global_atomic_add_f32 v[50:51], v47, off offset:4
	global_atomic_add_f32 v[50:51], v48, off offset:8
	global_atomic_add_f32 v[50:51], v49, off offset:12
	v_mul_f32_e32 v42, v42, v101
	v_mul_f32_e32 v43, v43, v101
	v_mul_f32_e32 v44, v44, v101
	v_mul_f32_e32 v45, v45, v101
	v_mul_f32_e32 v38, v38, v101
	v_mul_f32_e32 v39, v39, v101
	v_mul_f32_e32 v40, v40, v101
	v_mul_f32_e32 v41, v41, v101
	v_mul_f32_e32 v34, v34, v101
	v_mul_f32_e32 v35, v35, v101
	v_mul_f32_e32 v36, v36, v101
	v_mul_f32_e32 v37, v37, v101
	v_lshlrev_b32_e32 v48, 16, v114
	v_and_b32_e32 v46, 0xffff0000, v114
	v_lshlrev_b32_e32 v49, 16, v115
	v_and_b32_e32 v47, 0xffff0000, v115
	v_mul_f32_e32 v42, v42, v48
	v_mul_f32_e32 v43, v43, v46
	v_mul_f32_e32 v44, v44, v49
	v_mul_f32_e32 v45, v45, v47
	global_atomic_add_f32 v[50:51], v42, off offset:64
	global_atomic_add_f32 v[50:51], v43, off offset:68
	global_atomic_add_f32 v[50:51], v44, off offset:72
	global_atomic_add_f32 v[50:51], v45, off offset:76
	v_lshlrev_b32_e32 v44, 16, v116
	v_and_b32_e32 v42, 0xffff0000, v116
	v_lshlrev_b32_e32 v45, 16, v117
	v_and_b32_e32 v43, 0xffff0000, v117
	v_mul_f32_e32 v38, v38, v44
	v_mul_f32_e32 v39, v39, v42
	v_mul_f32_e32 v40, v40, v45
	v_mul_f32_e32 v41, v41, v43
	global_atomic_add_f32 v[50:51], v38, off offset:512
	global_atomic_add_f32 v[50:51], v39, off offset:516
	global_atomic_add_f32 v[50:51], v40, off offset:520
	global_atomic_add_f32 v[50:51], v41, off offset:524
	v_or_b32_e32 v38, 32, v72
	v_ashrrev_i32_e32 v39, 31, v38
	v_lshl_add_u64 v[42:43], v[38:39], 2, s[14:15]
	v_lshlrev_b64 v[38:39], 11, v[38:39]
	v_lshl_add_u64 v[38:39], s[12:13], 0, v[38:39]
	v_lshl_add_u64 v[38:39], v[38:39], 0, v[74:75]
	v_lshlrev_b32_e32 v44, 16, v118
	v_and_b32_e32 v40, 0xffff0000, v118
	v_lshlrev_b32_e32 v45, 16, v119
	v_and_b32_e32 v41, 0xffff0000, v119
	v_mul_f32_e32 v34, v34, v44
	v_mul_f32_e32 v35, v35, v40
	v_mul_f32_e32 v36, v36, v45
	v_mul_f32_e32 v37, v37, v41
	global_atomic_add_f32 v[50:51], v34, off offset:576
	global_atomic_add_f32 v[50:51], v35, off offset:580
	global_atomic_add_f32 v[50:51], v36, off offset:584
	global_atomic_add_f32 v[50:51], v37, off offset:588
	s_nop 0
	v_add_co_u32_e32 v40, vcc, s27, v70
	v_lshl_add_u64 v[34:35], v[70:71], 0, s[44:45]
	s_nop 0
	v_addc_co_u32_e32 v41, vcc, -1, v71, vcc
	s_mov_b32 s44, 0xf0030000
	s_mov_b32 s45, -1
	v_mul_f32_e32 v30, v30, v102
	v_lshlrev_b32_e32 v43, 16, v120
	v_mul_f32_e32 v31, v31, v102
	v_and_b32_e32 v36, 0xffff0000, v120
	v_mul_f32_e32 v32, v32, v102
	v_lshlrev_b32_e32 v44, 16, v121
	v_mul_f32_e32 v33, v33, v102
	v_and_b32_e32 v37, 0xffff0000, v121
	v_mul_f32_e32 v30, v30, v43
	v_mul_f32_e32 v31, v31, v36
	v_mul_f32_e32 v32, v32, v44
	v_mul_f32_e32 v33, v33, v37
	global_atomic_add_f32 v[40:41], v30, off
	global_atomic_add_f32 v[34:35], v31, off offset:4
	global_atomic_add_f32 v[34:35], v32, off offset:8
	global_atomic_add_f32 v[34:35], v33, off offset:12
	v_mul_f32_e32 v26, v26, v102
	v_mul_f32_e32 v27, v27, v102
	v_mul_f32_e32 v28, v28, v102
	v_mul_f32_e32 v29, v29, v102
	v_mul_f32_e32 v22, v22, v102
	v_mul_f32_e32 v23, v23, v102
	v_mul_f32_e32 v24, v24, v102
	v_mul_f32_e32 v25, v25, v102
	v_mul_f32_e32 v18, v18, v102
	v_mul_f32_e32 v19, v19, v102
	v_mul_f32_e32 v20, v20, v102
	v_mul_f32_e32 v21, v21, v102
	v_lshlrev_b32_e32 v32, 16, v122
	v_and_b32_e32 v30, 0xffff0000, v122
	v_lshlrev_b32_e32 v33, 16, v123
	v_and_b32_e32 v31, 0xffff0000, v123
	v_mul_f32_e32 v26, v26, v32
	v_mul_f32_e32 v27, v27, v30
	v_mul_f32_e32 v28, v28, v33
	v_mul_f32_e32 v29, v29, v31
;     __device__ __forceinline__ void operator()(const f32x4 (&acc)[2][2][4][2], const Unit& u, int wr, int wc, int fr, int fq) const {
;     ...
;         for (int m = 0; m < 4; ++m) {
;             const int row = u.pm * BM + wr * 64 + m * 16 + fr;
;             const float rs = rstd[row];
; #pragma unroll
;             for (int bj = 0; bj < 2; ++bj)
; #pragma unroll
;                 for (int n = 0; n < 2; ++n) {
;                     const int c = col0 + bj * HALF + n * 16;
;                     const u32x2e gw = *(const u32x2e*)(GS + (size_t)row * 1024 + c);
;                     const f32x4 a = acc[0][bj][m][n]; float* p = T1 + (size_t)(row - P_ROWS) * 1024 + c;
;                     __hip_atomic_fetch_add(p + 0, a[0] * rs * bf_lo(gw.x), __ATOMIC_RELAXED, __HIP_MEMORY_SCOPE_AGENT); __hip_atomic_fetch_add(p + 1, a[1] * rs * bf_hi(gw.x), __ATOMIC_RELAXED, __HIP_MEMORY_SCOPE_AGENT);
;                     __hip_atomic_fetch_add(p + 2, a[2] * rs * bf_lo(gw.y), __ATOMIC_RELAXED, __HIP_MEMORY_SCOPE_AGENT); __hip_atomic_fetch_add(p + 3, a[3] * rs * bf_hi(gw.y), __ATOMIC_RELAXED, __HIP_MEMORY_SCOPE_AGENT);
;                 }
;         }
	global_atomic_add_f32 v[34:35], v26, off offset:64
	global_atomic_add_f32 v[34:35], v27, off offset:68
	global_atomic_add_f32 v[34:35], v28, off offset:72
	global_atomic_add_f32 v[34:35], v29, off offset:76
	v_lshlrev_b32_e32 v28, 16, v124
	v_and_b32_e32 v26, 0xffff0000, v124
	v_lshlrev_b32_e32 v29, 16, v125
	v_and_b32_e32 v27, 0xffff0000, v125
	v_mul_f32_e32 v22, v22, v28
	v_mul_f32_e32 v23, v23, v26
	v_mul_f32_e32 v24, v24, v29
	v_mul_f32_e32 v25, v25, v27
	global_atomic_add_f32 v[34:35], v22, off offset:512
	global_atomic_add_f32 v[34:35], v23, off offset:516
	global_atomic_add_f32 v[34:35], v24, off offset:520
	global_atomic_add_f32 v[34:35], v25, off offset:524
	v_or_b32_e32 v22, 48, v72
	v_ashrrev_i32_e32 v23, 31, v22
	v_lshl_add_u64 v[26:27], v[22:23], 2, s[14:15]
	v_lshlrev_b64 v[22:23], 11, v[22:23]
	v_lshl_add_u64 v[22:23], s[12:13], 0, v[22:23]
	v_lshl_add_u64 v[22:23], v[22:23], 0, v[74:75]
	v_lshlrev_b32_e32 v28, 16, v126
	v_and_b32_e32 v24, 0xffff0000, v126
	v_lshlrev_b32_e32 v29, 16, v127
	v_and_b32_e32 v25, 0xffff0000, v127
	v_mul_f32_e32 v18, v18, v28
	v_mul_f32_e32 v19, v19, v24
	v_mul_f32_e32 v20, v20, v29
	v_mul_f32_e32 v21, v21, v25
	global_atomic_add_f32 v[34:35], v18, off offset:576
	global_atomic_add_f32 v[34:35], v19, off offset:580
	global_atomic_add_f32 v[34:35], v20, off offset:584
	global_atomic_add_f32 v[34:35], v21, off offset:588
	s_nop 0
	v_add_co_u32_e32 v24, vcc, s63, v70
	v_lshl_add_u64 v[18:19], v[70:71], 0, s[44:45]
	s_nop 0
	v_addc_co_u32_e32 v25, vcc, -1, v71, vcc
	s_andn2_b64 vcc, exec, s[36:37]
	s_mov_b64 s[36:37], -1
	v_mul_f32_e32 v14, v14, v103
	v_lshlrev_b32_e32 v27, 16, v128
	v_mul_f32_e32 v15, v15, v103
	v_and_b32_e32 v20, 0xffff0000, v128
	v_mul_f32_e32 v16, v16, v103
	v_lshlrev_b32_e32 v28, 16, v129
	v_mul_f32_e32 v17, v17, v103
	v_and_b32_e32 v21, 0xffff0000, v129
	v_mul_f32_e32 v14, v14, v27
	v_mul_f32_e32 v15, v15, v20
	v_mul_f32_e32 v16, v16, v28
	v_mul_f32_e32 v17, v17, v21
	global_atomic_add_f32 v[24:25], v14, off
	global_atomic_add_f32 v[18:19], v15, off offset:4
	global_atomic_add_f32 v[18:19], v16, off offset:8
	global_atomic_add_f32 v[18:19], v17, off offset:12
	v_mul_f32_e32 v10, v10, v103
	v_mul_f32_e32 v11, v11, v103
	v_mul_f32_e32 v12, v12, v103
	v_mul_f32_e32 v13, v13, v103
	v_mul_f32_e32 v6, v6, v103
	v_mul_f32_e32 v7, v7, v103
	v_mul_f32_e32 v8, v8, v103
	v_mul_f32_e32 v9, v9, v103
	v_mul_f32_e32 v2, v2, v103
	v_mul_f32_e32 v3, v3, v103
	v_mul_f32_e32 v4, v4, v103
	v_mul_f32_e32 v5, v5, v103
	v_lshlrev_b32_e32 v16, 16, v130
	v_and_b32_e32 v14, 0xffff0000, v130
	v_lshlrev_b32_e32 v17, 16, v131
	v_and_b32_e32 v15, 0xffff0000, v131
	v_mul_f32_e32 v10, v10, v16
	v_mul_f32_e32 v11, v11, v14
	v_mul_f32_e32 v12, v12, v17
	v_mul_f32_e32 v13, v13, v15
	global_atomic_add_f32 v[18:19], v10, off offset:64
	global_atomic_add_f32 v[18:19], v11, off offset:68
	global_atomic_add_f32 v[18:19], v12, off offset:72
	global_atomic_add_f32 v[18:19], v13, off offset:76
	v_lshlrev_b32_e32 v12, 16, v132
	v_and_b32_e32 v10, 0xffff0000, v132
	v_lshlrev_b32_e32 v13, 16, v133
	v_and_b32_e32 v11, 0xffff0000, v133
	v_mul_f32_e32 v6, v6, v12
	v_mul_f32_e32 v7, v7, v10
	v_mul_f32_e32 v8, v8, v13
	v_mul_f32_e32 v9, v9, v11
	global_atomic_add_f32 v[18:19], v6, off offset:512
	global_atomic_add_f32 v[18:19], v7, off offset:516
	global_atomic_add_f32 v[18:19], v8, off offset:520
	global_atomic_add_f32 v[18:19], v9, off offset:524
	v_lshlrev_b32_e32 v8, 16, v134
	v_and_b32_e32 v6, 0xffff0000, v134
	v_lshlrev_b32_e32 v9, 16, v135
	v_mul_f32_e32 v2, v2, v8
	v_and_b32_e32 v7, 0xffff0000, v135
	v_mul_f32_e32 v3, v3, v6
	v_mul_f32_e32 v4, v4, v9
	global_atomic_add_f32 v[18:19], v2, off offset:576
	global_atomic_add_f32 v[18:19], v3, off offset:580
	global_atomic_add_f32 v[18:19], v4, off offset:584
	v_mul_f32_e32 v2, v5, v7
	global_atomic_add_f32 v[18:19], v2, off offset:588
	s_cbranch_vccnz .LBB0_1522
	s_andn2_b64 vcc, exec, s[4:5]
	s_cbranch_vccnz .LBB0_1521
	s_barrier
	s_branch .LBB0_1521
